# a4 + XPREP two rows per iteration with 8 loads in flight
# baseline (speedup 1.0000x reference)
.LBB0_116:
	s_add_u32 s64, s44, 0x3800000
	s_addc_u32 s65, s45, 0
	s_add_u32 s10, s44, 0x35c00000
	s_addc_u32 s11, s45, 0
	s_cmp_lt_i32 s46, 2
	s_cselect_b64 s[0:1], -1, 0
	s_cmp_gt_i32 s47, 1
	s_cselect_b64 s[2:3], -1, 0
	s_and_b64 s[4:5], s[0:1], s[2:3]
	s_andn2_b64 vcc, exec, s[4:5]
	s_cbranch_vccnz .LBB0_123
	v_lshrrev_b32_e32 v0, 6, v188
	v_lshl_add_u32 v0, s33, 3, v0
	s_mov_b32 s0, 0x10000
	v_cmp_gt_i32_e32 vcc, s0, v0
	s_and_saveexec_b64 s[2:3], vcc
	s_cbranch_execz .LBB0_122
	v_and_b32_e32 v1, 63, v188
	v_readlane_b32 s16, v235, 5
	v_lshlrev_b32_e32 v4, 5, v1
	v_mov_b32_e32 v5, 0
	v_readlane_b32 s17, v235, 6
	v_cmp_eq_u32_e32 vcc, 0, v1
	s_lshl_b32 s12, s66, 3
	v_lshl_add_u64 v[2:3], s[16:17], 0, v[4:5]
	v_lshlrev_b32_e32 v4, 4, v1
	v_mbcnt_lo_u32_b32 v1, -1, 0
	v_mbcnt_hi_u32_b32 v6, -1, v1
	v_and_b32_e32 v1, 64, v6
	v_lshl_add_u64 v[4:5], s[64:65], 0, v[4:5]
	s_mov_b64 s[6:7], 0
	v_add_u32_e32 v7, 64, v1
	v_xor_b32_e32 v8, 32, v6
	v_xor_b32_e32 v9, 16, v6
	v_xor_b32_e32 v10, 8, v6
	v_xor_b32_e32 v11, 4, v6
	v_xor_b32_e32 v12, 2, v6
	v_xor_b32_e32 v13, 1, v6
	v_mov_b32_e32 v14, 0x358637bd
	s_mov_b32 s13, 0x800000
	s_mov_b32 s14, 0xffff
	v_readlane_b32 s18, v235, 7
	v_readlane_b32 s19, v235, 8
	v_readlane_b32 s20, v235, 9
	v_readlane_b32 s21, v235, 10
	v_readlane_b32 s22, v235, 11
	v_readlane_b32 s23, v235, 12
	v_readlane_b32 s24, v235, 13
	v_readlane_b32 s25, v235, 14
	v_readlane_b32 s26, v235, 15
	v_readlane_b32 s27, v235, 16
	v_readlane_b32 s28, v235, 17
	v_readlane_b32 s29, v235, 18
	v_readlane_b32 s30, v235, 19
	v_readlane_b32 s31, v235, 20
	v_cmp_lt_i32_e64 s[0:1], v8, v7
	s_nop 1
	v_cndmask_b32_e64 v56, v6, v8, s[0:1]
	v_lshlrev_b32_e32 v56, 2, v56
	v_cmp_lt_i32_e64 s[0:1], v9, v7
	s_nop 1
	v_cndmask_b32_e64 v57, v6, v9, s[0:1]
	v_lshlrev_b32_e32 v57, 2, v57
	v_cmp_lt_i32_e64 s[0:1], v10, v7
	s_nop 1
	v_cndmask_b32_e64 v58, v6, v10, s[0:1]
	v_lshlrev_b32_e32 v58, 2, v58
	v_cmp_lt_i32_e64 s[0:1], v11, v7
	s_nop 1
	v_cndmask_b32_e64 v59, v6, v11, s[0:1]
	v_lshlrev_b32_e32 v59, 2, v59
	v_cmp_lt_i32_e64 s[0:1], v12, v7
	s_nop 1
	v_cndmask_b32_e64 v60, v6, v12, s[0:1]
	v_lshlrev_b32_e32 v60, 2, v60
	v_cmp_lt_i32_e64 s[0:1], v13, v7
	s_nop 1
	v_cndmask_b32_e64 v61, v6, v13, s[0:1]
	v_lshlrev_b32_e32 v61, 2, v61
.Lxp_loop:
	v_ashrrev_i32_e32 v1, 31, v0
	v_lshlrev_b64 v[16:17], 12, v[0:1]
	v_lshl_add_u64 v[32:33], v[2:3], 0, v[16:17]
	global_load_dwordx4 v[16:19], v[32:33], off nt
	global_load_dwordx4 v[20:23], v[32:33], off offset:16 nt
	global_load_dwordx4 v[24:27], v[32:33], off offset:2048 nt
	global_load_dwordx4 v[28:31], v[32:33], off offset:2064 nt
	v_add_u32_e32 v36, s12, v0
	v_cmp_lt_i32_e64 s[0:1], s14, v36
	s_nop 1
	v_cndmask_b32_e64 v36, v36, v0, s[0:1]
	v_ashrrev_i32_e32 v37, 31, v36
	v_lshlrev_b64 v[38:39], 12, v[36:37]
	v_lshl_add_u64 v[38:39], v[2:3], 0, v[38:39]
	global_load_dwordx4 v[40:43], v[38:39], off nt
	global_load_dwordx4 v[44:47], v[38:39], off offset:16 nt
	global_load_dwordx4 v[48:51], v[38:39], off offset:2048 nt
	global_load_dwordx4 v[52:55], v[38:39], off offset:2064 nt
	v_lshlrev_b64 v[34:35], 11, v[0:1]
	v_lshl_add_u64 v[34:35], v[4:5], 0, v[34:35]
	v_lshlrev_b64 v[62:63], 11, v[36:37]
	v_lshl_add_u64 v[62:63], v[4:5], 0, v[62:63]
	s_waitcnt vmcnt(4)
	v_cvt_pk_bf16_f32 v64, v16, v17
	v_cvt_pk_bf16_f32 v65, v18, v19
	v_cvt_pk_bf16_f32 v66, v20, v21
	v_cvt_pk_bf16_f32 v67, v22, v23
	v_cvt_pk_bf16_f32 v68, v24, v25
	v_cvt_pk_bf16_f32 v69, v26, v27
	v_cvt_pk_bf16_f32 v70, v28, v29
	v_cvt_pk_bf16_f32 v71, v30, v31
	v_mul_f32_e32 v84, v17, v17
	v_mul_f32_e32 v85, v19, v19
	v_mul_f32_e32 v86, v21, v21
	v_mul_f32_e32 v87, v23, v23
	v_fmac_f32_e32 v84, v16, v16
	v_fmac_f32_e32 v85, v18, v18
	v_fmac_f32_e32 v86, v20, v20
	v_fmac_f32_e32 v87, v22, v22
	v_add_f32_e32 v84, v84, v85
	v_add_f32_e32 v86, v86, v87
	v_add_f32_e32 v80, v84, v86
	v_mul_f32_e32 v84, v25, v25
	v_mul_f32_e32 v85, v27, v27
	v_mul_f32_e32 v86, v29, v29
	v_mul_f32_e32 v87, v31, v31
	v_fmac_f32_e32 v84, v24, v24
	v_fmac_f32_e32 v85, v26, v26
	v_fmac_f32_e32 v86, v28, v28
	v_fmac_f32_e32 v87, v30, v30
	v_add_f32_e32 v84, v84, v85
	v_add_f32_e32 v86, v86, v87
	v_add_f32_e32 v84, v84, v86
	v_add_f32_e32 v80, v80, v84
	s_waitcnt vmcnt(0)
	v_cvt_pk_bf16_f32 v72, v40, v41
	v_cvt_pk_bf16_f32 v73, v42, v43
	v_cvt_pk_bf16_f32 v74, v44, v45
	v_cvt_pk_bf16_f32 v75, v46, v47
	v_cvt_pk_bf16_f32 v76, v48, v49
	v_cvt_pk_bf16_f32 v77, v50, v51
	v_cvt_pk_bf16_f32 v78, v52, v53
	v_cvt_pk_bf16_f32 v79, v54, v55
	v_mul_f32_e32 v84, v41, v41
	v_mul_f32_e32 v85, v43, v43
	v_mul_f32_e32 v86, v45, v45
	v_mul_f32_e32 v87, v47, v47
	v_fmac_f32_e32 v84, v40, v40
	v_fmac_f32_e32 v85, v42, v42
	v_fmac_f32_e32 v86, v44, v44
	v_fmac_f32_e32 v87, v46, v46
	v_add_f32_e32 v84, v84, v85
	v_add_f32_e32 v86, v86, v87
	v_add_f32_e32 v81, v84, v86
	v_mul_f32_e32 v84, v49, v49
	v_mul_f32_e32 v85, v51, v51
	v_mul_f32_e32 v86, v53, v53
	v_mul_f32_e32 v87, v55, v55
	v_fmac_f32_e32 v84, v48, v48
	v_fmac_f32_e32 v85, v50, v50
	v_fmac_f32_e32 v86, v52, v52
	v_fmac_f32_e32 v87, v54, v54
	v_add_f32_e32 v84, v84, v85
	v_add_f32_e32 v86, v86, v87
	v_add_f32_e32 v84, v84, v86
	v_add_f32_e32 v81, v81, v84
	global_store_dwordx4 v[34:35], v[64:67], off
	global_store_dwordx4 v[34:35], v[68:71], off offset:1024
	global_store_dwordx4 v[62:63], v[72:75], off
	global_store_dwordx4 v[62:63], v[76:79], off offset:1024
	ds_bpermute_b32 v82, v56, v80
	ds_bpermute_b32 v83, v56, v81
	s_waitcnt lgkmcnt(1)
	v_add_f32_e32 v80, v80, v82
	s_waitcnt lgkmcnt(0)
	v_add_f32_e32 v81, v81, v83
	ds_bpermute_b32 v82, v57, v80
	ds_bpermute_b32 v83, v57, v81
	s_waitcnt lgkmcnt(1)
	v_add_f32_e32 v80, v80, v82
	s_waitcnt lgkmcnt(0)
	v_add_f32_e32 v81, v81, v83
	ds_bpermute_b32 v82, v58, v80
	ds_bpermute_b32 v83, v58, v81
	s_waitcnt lgkmcnt(1)
	v_add_f32_e32 v80, v80, v82
	s_waitcnt lgkmcnt(0)
	v_add_f32_e32 v81, v81, v83
	ds_bpermute_b32 v82, v59, v80
	ds_bpermute_b32 v83, v59, v81
	s_waitcnt lgkmcnt(1)
	v_add_f32_e32 v80, v80, v82
	s_waitcnt lgkmcnt(0)
	v_add_f32_e32 v81, v81, v83
	ds_bpermute_b32 v82, v60, v80
	ds_bpermute_b32 v83, v60, v81
	s_waitcnt lgkmcnt(1)
	v_add_f32_e32 v80, v80, v82
	s_waitcnt lgkmcnt(0)
	v_add_f32_e32 v81, v81, v83
	ds_bpermute_b32 v82, v61, v80
	ds_bpermute_b32 v83, v61, v81
	s_waitcnt lgkmcnt(1)
	v_add_f32_e32 v80, v80, v82
	s_waitcnt lgkmcnt(0)
	v_add_f32_e32 v81, v81, v83
	s_and_saveexec_b64 s[8:9], vcc
	s_cbranch_execz .Lxp_skip
	v_fmamk_f32 v80, v80, 0x3a800000, v14
	v_mul_f32_e32 v84, 0x4b800000, v80
	v_cmp_gt_f32_e64 s[0:1], s13, v80
	s_nop 1
	v_cndmask_b32_e64 v80, v80, v84, s[0:1]
	v_rsq_f32_e32 v80, v80
	s_nop 0
	v_mul_f32_e32 v84, 0x45800000, v80
	v_cndmask_b32_e64 v80, v80, v84, s[0:1]
	v_lshl_add_u64 v[86:87], v[0:1], 2, s[10:11]
	global_store_dword v[86:87], v80, off
	v_fmamk_f32 v81, v81, 0x3a800000, v14
	v_mul_f32_e32 v85, 0x4b800000, v81
	v_cmp_gt_f32_e64 s[0:1], s13, v81
	s_nop 1
	v_cndmask_b32_e64 v81, v81, v85, s[0:1]
	v_rsq_f32_e32 v81, v81
	s_nop 0
	v_mul_f32_e32 v85, 0x45800000, v81
	v_cndmask_b32_e64 v81, v81, v85, s[0:1]
	v_lshl_add_u64 v[86:87], v[36:37], 2, s[10:11]
	global_store_dword v[86:87], v81, off
.Lxp_skip:
	s_or_b64 exec, exec, s[8:9]
	v_add_u32_e32 v0, s12, v0
	v_add_u32_e32 v0, s12, v0
	v_cmp_lt_i32_e64 s[0:1], s14, v0
	s_or_b64 s[6:7], s[0:1], s[6:7]
	s_andn2_b64 exec, exec, s[6:7]
	s_cbranch_execnz .Lxp_loop
